# additionally GEMM1: every other CU of each XCD starts the phase 3 us late
# baseline (speedup 1.0000x reference)
.LBB0_202:
	s_cmp_lt_i32 s64, 3
	s_cselect_b64 s[16:17], -1, 0
	s_and_b64 s[0:1], s[16:17], s[0:1]
	s_xor_b64 s[0:1], s[0:1], -1
	s_cmpk_gt_i32 s2, 0x6ff
	s_cselect_b64 s[4:5], -1, 0
	s_or_b64 s[0:1], s[0:1], s[4:5]
	s_and_b64 vcc, exec, s[0:1]
	v_mbcnt_lo_u32_b32 v213, -1, 0
	s_cbranch_vccnz .LBB0_386
	v_and_b32_e32 v176, 63, v212
	v_and_b32_e32 v177, 31, v212
	v_bfe_u32 v178, v212, 5, 1
	v_lshrrev_b32_e32 v179, 6, v212
	v_mul_u32_u24_e32 v179, 0x1200, v179
	v_add_u32_e32 v179, 0x12000, v179
	v_mul_u32_u24_e32 v180, 0x90, v177
	v_add_u32_e32 v180, v180, v179
	v_lshl_add_u32 v202, v178, 6, v180
	v_lshl_add_u32 v203, v178, 5, v180
	v_lshrrev_b32_e32 v181, 3, v176
	v_and_b32_e32 v182, 7, v176
	v_mul_u32_u24_e32 v183, 0x240, v181
	v_add_u32_e32 v183, v183, v179
	v_lshl_add_u32 v204, v182, 4, v183
	v_lshrrev_b32_e32 v184, 2, v176
	v_and_b32_e32 v185, 3, v176
	v_mul_u32_u24_e32 v186, 0x120, v184
	v_add_u32_e32 v186, v186, v179
	v_lshl_add_u32 v205, v185, 4, v186
	v_lshlrev_b32_e32 v187, 2, v181
	v_sub_u32_e32 v187, v187, v177
	v_lshlrev_b32_e32 v188, 4, v182
	v_lshlrev_b32_e32 v189, 6, v178
	v_sub_u32_e32 v188, v188, v189
	v_lshl_add_u32 v206, v187, 10, v188
	v_ashrrev_i32_e32 v207, 31, v206
	v_lshl_add_u32 v208, v187, 7, v188
	v_ashrrev_i32_e32 v209, 31, v208
	v_lshlrev_b32_e32 v190, 1, v184
	v_sub_u32_e32 v190, v190, v177
	v_lshlrev_b32_e32 v191, 4, v185
	v_lshlrev_b32_e32 v189, 5, v178
	v_sub_u32_e32 v191, v191, v189
	v_lshl_add_u32 v210, v190, 10, v191
	v_ashrrev_i32_e32 v211, 31, v210
	s_and_b32 s0, s62, 7
	s_cmp_lg_u32 s0, 0
	s_cselect_b64 s[0:1], -1, 0
	s_ashr_i32 s44, s62, 3
	s_add_u32 s45, s96, 0x20000
	s_addc_u32 s46, s97, 0
	s_add_u32 s47, s96, 0x13a0000
	s_addc_u32 s48, s97, 0
	s_add_u32 s18, s96, 0xd3a4000
	s_addc_u32 s19, s97, 0
	s_add_u32 s20, s96, 0x73a0000
	s_addc_u32 s21, s97, 0
	s_add_u32 s22, s96, 0x8ba0000
	s_addc_u32 s23, s97, 0
	s_add_u32 s24, s96, 0xa3a0000
	s_addc_u32 s25, s97, 0
	s_add_u32 s26, s74, 0x7000000
	s_addc_u32 s27, s75, 0
	s_add_u32 s28, s74, 0x6000000
	s_addc_u32 s29, s75, 0
	s_abs_i32 s49, s62
	v_cvt_f32_u32_e32 v2, s49
	s_sub_i32 s3, 0, s49
	v_cndmask_b32_e64 v3, 0, 1, s[0:1]
	s_mov_b64 s[72:73], s[60:61]
	v_rcp_iflag_f32_e32 v2, v2
	v_mov_b32_e32 v99, 0
	s_movk_i32 s50, 0x90
	v_cmp_ne_u32_e64 s[0:1], 1, v3
	v_mul_f32_e32 v2, 0x4f7ffffe, v2
	v_cvt_u32_f32_e32 v2, v2
	s_ashr_i32 s51, s62, 31
	s_sub_i32 s52, 0, s62
	s_mov_b32 s54, 0x20000
	v_readfirstlane_b32 s4, v2
	s_mul_i32 s3, s3, s4
	s_mul_hi_u32 s3, s4, s3
	s_add_i32 s53, s4, s3
	s_mov_b32 s55, 0x40000
	s_movk_i32 s56, 0x110
	s_movk_i32 s57, 0x2000
	v_mov_b32_e32 v124, 0x358637bd
	s_mov_b32 s58, 0x800000
	s_movk_i32 s59, 0x1fe0
	s_movk_i32 s60, 0x1fc0
	v_mov_b32_e32 v125, 0x60
	v_mov_b32_e32 v126, 0x440
	v_mov_b32_e32 v127, 0x880
	v_mov_b32_e32 v128, 0xfffffa00
	v_mov_b32_e32 v129, 0xfffff800
	v_mov_b32_e32 v130, 0x3e38aa3b
	v_mbcnt_hi_u32_b32 v132, -1, v213
	v_mov_b32_e32 v133, 0xbb9e800
	v_mov_b32_e32 v134, 0x5b9f800
	s_bitcmp1_b32 s2, 3
	s_cbranch_scc0 .Lskew_done_g1
	s_memrealtime s[98:99]
	s_waitcnt lgkmcnt(0)
	s_add_u32 s100, s98, 300

.Lskew_done_g1:
	s_mov_b32 s101, 0
	s_mov_b32 s61, s2
	s_branch .LBB0_205
